# vpre + fast-loop trims (no prefetch-index clamps below the diagonal, one vmcnt wait per store group)
# speedup vs baseline: 1.0235x; 1.0026x over previous
.Lfm_a_exp:
	v_exp_f32_e32 v34, v34
	v_exp_f32_e32 v50, v50
	v_exp_f32_e32 v35, v35
	v_exp_f32_e32 v51, v51
	v_exp_f32_e32 v42, v42
	v_exp_f32_e32 v58, v58
	v_exp_f32_e32 v43, v43
	v_exp_f32_e32 v59, v59
	v_exp_f32_e32 v36, v36
	v_exp_f32_e32 v52, v52
	v_exp_f32_e32 v37, v37
	v_exp_f32_e32 v53, v53
	v_exp_f32_e32 v44, v44
	v_exp_f32_e32 v60, v60
	v_exp_f32_e32 v45, v45
	v_exp_f32_e32 v61, v61
	v_exp_f32_e32 v38, v38
	v_exp_f32_e32 v54, v54
	v_exp_f32_e32 v39, v39
	v_exp_f32_e32 v55, v55
	v_exp_f32_e32 v46, v46
	v_exp_f32_e32 v62, v62
	v_exp_f32_e32 v47, v47
	v_exp_f32_e32 v63, v63
	v_exp_f32_e32 v40, v40
	v_exp_f32_e32 v56, v56
	v_exp_f32_e32 v41, v41
	v_exp_f32_e32 v57, v57
	v_exp_f32_e32 v48, v48
	v_exp_f32_e32 v64, v64
	v_exp_f32_e32 v49, v49
	v_exp_f32_e32 v65, v65
	v_pk_add_f32 v[122:123], v[34:35], v[50:51]
	v_pk_add_f32 v[124:125], v[36:37], v[52:53]
	v_pk_add_f32 v[126:127], v[38:39], v[54:55]
	v_pk_add_f32 v[128:129], v[40:41], v[56:57]
	v_pk_add_f32 v[130:131], v[42:43], v[58:59]
	v_pk_add_f32 v[132:133], v[44:45], v[60:61]
	v_pk_add_f32 v[134:135], v[46:47], v[62:63]
	v_pk_add_f32 v[136:137], v[48:49], v[64:65]
	v_pk_add_f32 v[122:123], v[122:123], v[124:125]
	v_pk_add_f32 v[126:127], v[126:127], v[128:129]
	v_pk_add_f32 v[130:131], v[130:131], v[132:133]
	v_pk_add_f32 v[134:135], v[134:135], v[136:137]
	v_pk_add_f32 v[122:123], v[122:123], v[126:127]
	v_pk_add_f32 v[130:131], v[130:131], v[134:135]
	v_pk_add_f32 v[122:123], v[122:123], v[130:131]
	v_add_f32_e32 v0, v122, v123
	v_cvt_pk_bf16_f32 v122, v34, v35
	v_cvt_pk_bf16_f32 v123, v36, v37
	v_cvt_pk_bf16_f32 v124, v38, v39
	v_cvt_pk_bf16_f32 v125, v40, v41
	v_cvt_pk_bf16_f32 v126, v42, v43
	v_cvt_pk_bf16_f32 v127, v44, v45
	v_cvt_pk_bf16_f32 v128, v46, v47
	v_cvt_pk_bf16_f32 v129, v48, v49
	v_cvt_pk_bf16_f32 v130, v50, v51
	v_cvt_pk_bf16_f32 v131, v52, v53
	v_cvt_pk_bf16_f32 v132, v54, v55
	v_cvt_pk_bf16_f32 v133, v56, v57
	v_cvt_pk_bf16_f32 v134, v58, v59
	v_cvt_pk_bf16_f32 v135, v60, v61
	v_cvt_pk_bf16_f32 v136, v62, v63
	v_cvt_pk_bf16_f32 v137, v64, v65
	v_add_f32_e32 v162, v162, v0
	s_waitcnt lgkmcnt(0)
	s_barrier
	v_mfma_f32_32x32x16_bf16 v[2:17], v[164:167], v[122:125], v[2:17]
	s_setprio 1
	v_add3_u32 v0, s57, v152, v153
	s_waitcnt vmcnt(3)
	ds_write_b128 v0, v[86:89]
	v_mfma_f32_32x32x16_bf16 v[18:33], v[168:171], v[122:125], v[18:33]
	v_add3_u32 v0, s57, v154, v155
	ds_write_b128 v0, v[90:93]
	v_mfma_f32_32x32x16_bf16 v[2:17], v[172:175], v[126:129], v[2:17]
	v_add3_u32 v0, s57, v156, v140
	ds_write_b128 v0, v[82:85] offset:13312
	v_add_u32_e32 v249, s60, v157
	v_mfma_f32_32x32x16_bf16 v[18:33], v[176:179], v[126:129], v[18:33]
	ds_read_b128 v[236:239], v249
	ds_read_b128 v[240:243], v249 offset:6656
	ds_read_b128 v[244:247], v249 offset:32
	v_mfma_f32_32x32x16_bf16 v[2:17], v[180:183], v[130:133], v[2:17]
	ds_read_b128 v[164:167], v249 offset:6688
	ds_read_b128 v[168:171], v249 offset:64
	ds_read_b128 v[172:175], v249 offset:6720
	v_mfma_f32_32x32x16_bf16 v[18:33], v[220:223], v[130:133], v[18:33]
	ds_read_b128 v[176:179], v249 offset:96
	ds_read_b128 v[180:183], v249 offset:6752
	ds_read_b128 v[220:223], v249 offset:128
	v_mfma_f32_32x32x16_bf16 v[2:17], v[224:227], v[134:137], v[2:17]
	ds_read_b128 v[224:227], v249 offset:6784
	v_mfma_f32_32x32x16_bf16 v[18:33], v[232:235], v[134:137], v[18:33]
	ds_read_b128 v[232:235], v249 offset:160
	s_waitcnt lgkmcnt(9)
	v_mfma_f32_32x32x16_bf16 v[34:49], v[236:239], v[196:199], v[66:81]
	ds_read_b128 v[236:239], v249 offset:6816
	s_add_i32 s0, s59, 4
	s_lshl_b32 s8, s0, 6
	v_mfma_f32_32x32x16_bf16 v[50:65], v[240:243], v[196:199], v[66:81]
	s_mul_i32 s0, s8, 0x600
	s_mov_b32 s1, 0
	s_waitcnt lgkmcnt(7)
	v_mfma_f32_32x32x16_bf16 v[34:49], v[244:247], v[200:203], v[34:49]
	v_add_u32_e32 v248, s60, v160
	v_lshl_add_u64 v[82:83], s[0:1], 0, v[186:187]
	v_lshl_add_u64 v[84:85], s[0:1], 0, v[188:189]
	v_mfma_f32_32x32x16_bf16 v[50:65], v[164:167], v[200:203], v[50:65]
	ds_read_b128 v[164:167], v248 offset:13312
	global_load_dwordx4 v[86:89], v[82:83], off
	global_load_dwordx4 v[90:93], v[84:85], off
	v_lshl_add_u64 v[82:83], s[8:9], 1, v[142:143]
	v_mfma_f32_32x32x16_bf16 v[34:49], v[168:171], v[204:207], v[34:49]
	ds_read_b128 v[168:171], v248 offset:17920
	global_load_dwordx4 v[82:85], v[82:83], off
	s_waitcnt lgkmcnt(6)
	v_mfma_f32_32x32x16_bf16 v[50:65], v[172:175], v[204:207], v[50:65]
	ds_read_b128 v[172:175], v248 offset:13344
	v_mfma_f32_32x32x16_bf16 v[34:49], v[176:179], v[208:211], v[34:49]
	ds_read_b128 v[176:179], v248 offset:17952
	v_mfma_f32_32x32x16_bf16 v[50:65], v[180:183], v[208:211], v[50:65]
	ds_read_b128 v[180:183], v248 offset:13376
	s_waitcnt lgkmcnt(6)
	v_mfma_f32_32x32x16_bf16 v[34:49], v[220:223], v[212:215], v[34:49]
	ds_read_b128 v[220:223], v248 offset:17984
	v_mfma_f32_32x32x16_bf16 v[50:65], v[224:227], v[212:215], v[50:65]
	ds_read_b128 v[224:227], v248 offset:13408
	v_mfma_f32_32x32x16_bf16 v[34:49], v[232:235], v[216:219], v[34:49]
	ds_read_b128 v[232:235], v248 offset:18016
	s_waitcnt lgkmcnt(8)
	v_mfma_f32_32x32x16_bf16 v[50:65], v[236:239], v[216:219], v[50:65]
	s_setprio 0
	s_waitcnt lgkmcnt(8)
	s_barrier
	v_max3_f32 v0, v34, v35, v36
	v_max3_f32 v106, v50, v51, v52
	v_max3_f32 v0, v0, v37, v38
	v_max3_f32 v106, v106, v53, v54
	v_max3_f32 v0, v0, v39, v40
	v_max3_f32 v106, v106, v55, v56
	v_max3_f32 v0, v0, v41, v42
	v_max3_f32 v106, v106, v57, v58
	v_max3_f32 v0, v0, v43, v44
	v_max3_f32 v106, v106, v59, v60
	v_max3_f32 v0, v0, v45, v46
	v_max3_f32 v106, v106, v61, v62
	v_max_f32_e32 v107, v65, v65
	v_max_f32_e32 v108, v49, v49
	v_max3_f32 v0, v0, v47, v48
	v_max3_f32 v106, v106, v63, v64
	v_max_f32_e32 v107, v108, v107
	v_max3_f32 v0, v0, v106, v107
	v_cmp_lt_f32_e32 vcc, s35, v0
	s_cbranch_vccnz .Lfm_b_resc
.Lfm_b_exp:
	v_exp_f32_e32 v34, v34
	v_exp_f32_e32 v50, v50
	v_exp_f32_e32 v35, v35
	v_exp_f32_e32 v51, v51
	v_exp_f32_e32 v42, v42
	v_exp_f32_e32 v58, v58
	v_exp_f32_e32 v43, v43
	v_exp_f32_e32 v59, v59
	v_exp_f32_e32 v36, v36
	v_exp_f32_e32 v52, v52
	v_exp_f32_e32 v37, v37
	v_exp_f32_e32 v53, v53
	v_exp_f32_e32 v44, v44
	v_exp_f32_e32 v60, v60
	v_exp_f32_e32 v45, v45
	v_exp_f32_e32 v61, v61
	v_exp_f32_e32 v38, v38
	v_exp_f32_e32 v54, v54
	v_exp_f32_e32 v39, v39
	v_exp_f32_e32 v55, v55
	v_exp_f32_e32 v46, v46
	v_exp_f32_e32 v62, v62
	v_exp_f32_e32 v47, v47
	v_exp_f32_e32 v63, v63
	v_exp_f32_e32 v40, v40
	v_exp_f32_e32 v56, v56
	v_exp_f32_e32 v41, v41
	v_exp_f32_e32 v57, v57
	v_exp_f32_e32 v48, v48
	v_exp_f32_e32 v64, v64
	v_exp_f32_e32 v49, v49
	v_exp_f32_e32 v65, v65
	v_pk_add_f32 v[106:107], v[34:35], v[50:51]
	v_pk_add_f32 v[108:109], v[36:37], v[52:53]
	v_pk_add_f32 v[110:111], v[38:39], v[54:55]
	v_pk_add_f32 v[112:113], v[40:41], v[56:57]
	v_pk_add_f32 v[114:115], v[42:43], v[58:59]
	v_pk_add_f32 v[116:117], v[44:45], v[60:61]
	v_pk_add_f32 v[118:119], v[46:47], v[62:63]
	v_pk_add_f32 v[120:121], v[48:49], v[64:65]
	v_pk_add_f32 v[106:107], v[106:107], v[108:109]
	v_pk_add_f32 v[110:111], v[110:111], v[112:113]
	v_pk_add_f32 v[114:115], v[114:115], v[116:117]
	v_pk_add_f32 v[118:119], v[118:119], v[120:121]
	v_pk_add_f32 v[106:107], v[106:107], v[110:111]
	v_pk_add_f32 v[114:115], v[114:115], v[118:119]
	v_pk_add_f32 v[106:107], v[106:107], v[114:115]
	v_add_f32_e32 v0, v106, v107
	v_cvt_pk_bf16_f32 v106, v34, v35
	v_cvt_pk_bf16_f32 v107, v36, v37
	v_cvt_pk_bf16_f32 v108, v38, v39
	v_cvt_pk_bf16_f32 v109, v40, v41
	v_cvt_pk_bf16_f32 v110, v42, v43
	v_cvt_pk_bf16_f32 v111, v44, v45
	v_cvt_pk_bf16_f32 v112, v46, v47
	v_cvt_pk_bf16_f32 v113, v48, v49
	v_cvt_pk_bf16_f32 v114, v50, v51
	v_cvt_pk_bf16_f32 v115, v52, v53
	v_cvt_pk_bf16_f32 v116, v54, v55
	v_cvt_pk_bf16_f32 v117, v56, v57
	v_cvt_pk_bf16_f32 v118, v58, v59
	v_cvt_pk_bf16_f32 v119, v60, v61
	v_cvt_pk_bf16_f32 v120, v62, v63
	v_cvt_pk_bf16_f32 v121, v64, v65
	v_add_f32_e32 v162, v162, v0
	s_waitcnt lgkmcnt(0)
	s_barrier
	v_mfma_f32_32x32x16_bf16 v[2:17], v[164:167], v[106:109], v[2:17]
	s_setprio 1
	v_add3_u32 v0, s58, v152, v153
	s_waitcnt vmcnt(3)
	ds_write_b128 v0, v[98:101]
	v_mfma_f32_32x32x16_bf16 v[18:33], v[168:171], v[106:109], v[18:33]
	v_add3_u32 v0, s58, v154, v155
	ds_write_b128 v0, v[94:97]
	v_mfma_f32_32x32x16_bf16 v[2:17], v[172:175], v[110:113], v[2:17]
	v_add3_u32 v0, s58, v156, v140
	ds_write_b128 v0, v[102:105] offset:13312
	v_add_u32_e32 v249, s57, v157
	v_mfma_f32_32x32x16_bf16 v[18:33], v[176:179], v[110:113], v[18:33]
	ds_read_b128 v[236:239], v249
	ds_read_b128 v[240:243], v249 offset:6656
	ds_read_b128 v[244:247], v249 offset:32
	v_mfma_f32_32x32x16_bf16 v[2:17], v[180:183], v[114:117], v[2:17]
	ds_read_b128 v[164:167], v249 offset:6688
	ds_read_b128 v[168:171], v249 offset:64
	ds_read_b128 v[172:175], v249 offset:6720
	v_mfma_f32_32x32x16_bf16 v[18:33], v[220:223], v[114:117], v[18:33]
	ds_read_b128 v[176:179], v249 offset:96
	ds_read_b128 v[180:183], v249 offset:6752
	ds_read_b128 v[220:223], v249 offset:128
	v_mfma_f32_32x32x16_bf16 v[2:17], v[224:227], v[118:121], v[2:17]
	ds_read_b128 v[224:227], v249 offset:6784
	s_add_i32 s59, s59, 2
	s_mov_b32 s0, s58
	v_mfma_f32_32x32x16_bf16 v[18:33], v[232:235], v[118:121], v[18:33]
	ds_read_b128 v[232:235], v249 offset:160
	s_mov_b32 s58, s57
	s_mov_b32 s57, s60
	s_mov_b32 s60, s0
	s_addk_i32 s54, 0x80
	s_waitcnt lgkmcnt(9)
	v_mfma_f32_32x32x16_bf16 v[34:49], v[236:239], v[196:199], v[66:81]
	ds_read_b128 v[236:239], v249 offset:6816
	s_add_i32 s1, s59, 3
	s_lshl_b32 s8, s1, 6
	v_mfma_f32_32x32x16_bf16 v[50:65], v[240:243], v[196:199], v[66:81]
	s_mul_i32 s20, s8, 0x600
	s_mov_b32 s21, 0
	s_waitcnt lgkmcnt(7)
	v_mfma_f32_32x32x16_bf16 v[34:49], v[244:247], v[200:203], v[34:49]
	v_add_u32_e32 v248, s58, v160
	v_lshl_add_u64 v[94:95], s[20:21], 0, v[186:187]
	v_lshl_add_u64 v[96:97], s[20:21], 0, v[188:189]
	v_mfma_f32_32x32x16_bf16 v[50:65], v[164:167], v[200:203], v[50:65]
	ds_read_b128 v[164:167], v248 offset:13312
	v_lshl_add_u64 v[102:103], s[8:9], 1, v[142:143]
	global_load_dwordx4 v[98:101], v[94:95], off
	s_nop 0
	v_mfma_f32_32x32x16_bf16 v[34:49], v[168:171], v[204:207], v[34:49]
	ds_read_b128 v[168:171], v248 offset:17920
	global_load_dwordx4 v[94:97], v[96:97], off
	global_load_dwordx4 v[102:105], v[102:103], off
	s_waitcnt lgkmcnt(6)
	v_mfma_f32_32x32x16_bf16 v[50:65], v[172:175], v[204:207], v[50:65]
	ds_read_b128 v[172:175], v248 offset:13344
	v_mfma_f32_32x32x16_bf16 v[34:49], v[176:179], v[208:211], v[34:49]
	ds_read_b128 v[176:179], v248 offset:17952
	v_mfma_f32_32x32x16_bf16 v[50:65], v[180:183], v[208:211], v[50:65]
	ds_read_b128 v[180:183], v248 offset:13376
	s_waitcnt lgkmcnt(6)
	v_mfma_f32_32x32x16_bf16 v[34:49], v[220:223], v[212:215], v[34:49]
	ds_read_b128 v[220:223], v248 offset:17984
	v_mfma_f32_32x32x16_bf16 v[50:65], v[224:227], v[212:215], v[50:65]
	ds_read_b128 v[224:227], v248 offset:13408
	v_mfma_f32_32x32x16_bf16 v[34:49], v[232:235], v[216:219], v[34:49]
	ds_read_b128 v[232:235], v248 offset:18016
	s_waitcnt lgkmcnt(8)
	v_mfma_f32_32x32x16_bf16 v[50:65], v[236:239], v[216:219], v[50:65]
	s_setprio 0
	s_add_i32 s4, s55, s59
	s_cmp_lt_i32 s4, -2
	s_waitcnt lgkmcnt(8)
	s_barrier
	s_cbranch_scc1 .Lfm_head
	s_mov_b32 s0, s58
	s_mov_b32 s58, s60
	s_branch .LBB0_1037

.Lfd_a_exp:
	v_exp_f32_e32 v80, v80
	v_exp_f32_e32 v96, v96
	v_exp_f32_e32 v81, v81
	v_exp_f32_e32 v97, v97
	v_exp_f32_e32 v88, v88
	v_exp_f32_e32 v104, v104
	v_exp_f32_e32 v89, v89
	v_exp_f32_e32 v105, v105
	v_exp_f32_e32 v82, v82
	v_exp_f32_e32 v98, v98
	v_exp_f32_e32 v83, v83
	v_exp_f32_e32 v99, v99
	v_exp_f32_e32 v90, v90
	v_exp_f32_e32 v106, v106
	v_exp_f32_e32 v91, v91
	v_exp_f32_e32 v107, v107
	v_exp_f32_e32 v84, v84
	v_exp_f32_e32 v100, v100
	v_exp_f32_e32 v85, v85
	v_exp_f32_e32 v101, v101
	v_exp_f32_e32 v92, v92
	v_exp_f32_e32 v108, v108
	v_exp_f32_e32 v93, v93
	v_exp_f32_e32 v109, v109
	v_exp_f32_e32 v86, v86
	v_exp_f32_e32 v102, v102
	v_exp_f32_e32 v87, v87
	v_exp_f32_e32 v103, v103
	v_exp_f32_e32 v94, v94
	v_exp_f32_e32 v110, v110
	v_exp_f32_e32 v95, v95
	v_exp_f32_e32 v111, v111
	v_pk_add_f32 v[156:157], v[80:81], v[96:97]
	v_pk_add_f32 v[158:159], v[82:83], v[98:99]
	v_pk_add_f32 v[160:161], v[84:85], v[100:101]
	v_pk_add_f32 v[162:163], v[86:87], v[102:103]
	v_pk_add_f32 v[164:165], v[88:89], v[104:105]
	v_pk_add_f32 v[166:167], v[90:91], v[106:107]
	v_pk_add_f32 v[168:169], v[92:93], v[108:109]
	v_pk_add_f32 v[170:171], v[94:95], v[110:111]
	v_pk_add_f32 v[156:157], v[156:157], v[158:159]
	v_pk_add_f32 v[160:161], v[160:161], v[162:163]
	v_pk_add_f32 v[164:165], v[164:165], v[166:167]
	v_pk_add_f32 v[168:169], v[168:169], v[170:171]
	v_pk_add_f32 v[156:157], v[156:157], v[160:161]
	v_pk_add_f32 v[164:165], v[164:165], v[168:169]
	v_pk_add_f32 v[156:157], v[156:157], v[164:165]
	v_add_f32_e32 v0, v156, v157
	v_cvt_pk_bf16_f32 v156, v80, v81
	v_cvt_pk_bf16_f32 v157, v82, v83
	v_cvt_pk_bf16_f32 v158, v84, v85
	v_cvt_pk_bf16_f32 v159, v86, v87
	v_cvt_pk_bf16_f32 v160, v88, v89
	v_cvt_pk_bf16_f32 v161, v90, v91
	v_cvt_pk_bf16_f32 v162, v92, v93
	v_cvt_pk_bf16_f32 v163, v94, v95
	v_cvt_pk_bf16_f32 v164, v96, v97
	v_cvt_pk_bf16_f32 v165, v98, v99
	v_cvt_pk_bf16_f32 v166, v100, v101
	v_cvt_pk_bf16_f32 v167, v102, v103
	v_cvt_pk_bf16_f32 v168, v104, v105
	v_cvt_pk_bf16_f32 v169, v106, v107
	v_cvt_pk_bf16_f32 v170, v108, v109
	v_cvt_pk_bf16_f32 v171, v110, v111
	v_add_f32_e32 v193, v193, v0
	s_waitcnt lgkmcnt(0)
	s_barrier
	v_mfma_f32_32x32x16_bf16 v[64:79], v[196:199], v[156:159], v[64:79]
	s_setprio 1
	v_add_u32_e32 v14, s50, v188
	s_waitcnt vmcnt(3)
	ds_write_b128 v14, v[136:139]
	v_mfma_f32_32x32x16_bf16 v[48:63], v[200:203], v[156:159], v[48:63]
	ds_read_b128 v[196:199], v248 offset:9280
	v_add_u32_e32 v14, s50, v186
	v_add_u32_e32 v15, v14, v175
	v_mfma_f32_32x32x16_bf16 v[32:47], v[204:207], v[156:159], v[32:47]
	ds_read_b128 v[200:203], v248 offset:13888
	v_add_u32_e32 v14, v14, v187
	ds_write_b128 v15, v[128:131] offset:9216
	v_mfma_f32_32x32x16_bf16 v[16:31], v[208:211], v[156:159], v[16:31]
	ds_read_b128 v[204:207], v248 offset:18496
	ds_write_b128 v14, v[132:135] offset:9216
	v_mfma_f32_32x32x16_bf16 v[64:79], v[212:215], v[160:163], v[64:79]
	ds_read_b128 v[208:211], v248 offset:23104
	v_add_u32_e32 v249, s55, v190
	v_mfma_f32_32x32x16_bf16 v[48:63], v[216:219], v[160:163], v[48:63]
	ds_read_b128 v[212:215], v248 offset:9312
	v_mfma_f32_32x32x16_bf16 v[32:47], v[220:223], v[160:163], v[32:47]
	ds_read_b128 v[216:219], v248 offset:13920
	v_mfma_f32_32x32x16_bf16 v[16:31], v[224:227], v[160:163], v[16:31]
	ds_read_b128 v[220:223], v248 offset:18528
	ds_read_b128 v[224:227], v248 offset:23136
	s_waitcnt lgkmcnt(4)
	v_mfma_f32_32x32x16_bf16 v[64:79], v[196:199], v[164:167], v[64:79]
	ds_read_b128 v[196:199], v249
	s_add_i32 s0, s54, 4
	s_lshl_b32 s8, s0, 6
	v_mfma_f32_32x32x16_bf16 v[48:63], v[200:203], v[164:167], v[48:63]
	ds_read_b128 v[200:203], v249 offset:4608
	v_add_u32_e32 v14, s8, v174
	v_ashrrev_i32_e32 v15, 31, v14
	v_mfma_f32_32x32x16_bf16 v[32:47], v[204:207], v[164:167], v[32:47]
	ds_read_b128 v[204:207], v249 offset:32
	v_lshlrev_b64 v[14:15], 10, v[14:15]
	v_lshl_add_u64 v[132:133], s[8:9], 1, v[176:177]
	v_mfma_f32_32x32x16_bf16 v[16:31], v[208:211], v[164:167], v[16:31]
	ds_read_b128 v[208:211], v249 offset:4640
	v_lshl_add_u64 v[14:15], v[182:183], 0, v[14:15]
	v_lshl_add_u64 v[128:129], v[132:133], 0, v[178:179]
	s_waitcnt lgkmcnt(4)
	v_mfma_f32_32x32x16_bf16 v[64:79], v[212:215], v[168:171], v[64:79]
	ds_read_b128 v[212:215], v249 offset:64
	global_load_dwordx4 v[136:139], v[14:15], off
	s_nop 0
	v_mfma_f32_32x32x16_bf16 v[48:63], v[216:219], v[168:171], v[48:63]
	ds_read_b128 v[216:219], v249 offset:4672
	global_load_dwordx4 v[128:131], v[128:129], off
	v_lshl_add_u64 v[14:15], v[132:133], 0, v[180:181]
	v_mfma_f32_32x32x16_bf16 v[32:47], v[220:223], v[168:171], v[32:47]
	ds_read_b128 v[220:223], v249 offset:96
	global_load_dwordx4 v[132:135], v[14:15], off
	v_mfma_f32_32x32x16_bf16 v[16:31], v[224:227], v[168:171], v[16:31]
	ds_read_b128 v[224:227], v249 offset:4704
	v_add_u32_e32 v248, s55, v190
	s_waitcnt lgkmcnt(4)
	v_mfma_f32_32x32x16_bf16 v[80:95], v[196:199], v[232:235], v[112:127]
	ds_read_b128 v[196:199], v248 offset:9216
	v_mfma_f32_32x32x16_bf16 v[96:111], v[200:203], v[232:235], v[112:127]
	ds_read_b128 v[200:203], v248 offset:13824
	v_mfma_f32_32x32x16_bf16 v[80:95], v[204:207], v[236:239], v[80:95]
	ds_read_b128 v[204:207], v248 offset:18432
	v_mfma_f32_32x32x16_bf16 v[96:111], v[208:211], v[236:239], v[96:111]
	ds_read_b128 v[208:211], v248 offset:23040
	s_waitcnt lgkmcnt(4)
	v_mfma_f32_32x32x16_bf16 v[80:95], v[212:215], v[240:243], v[80:95]
	ds_read_b128 v[212:215], v248 offset:9248
	v_mfma_f32_32x32x16_bf16 v[96:111], v[216:219], v[240:243], v[96:111]
	ds_read_b128 v[216:219], v248 offset:13856
	v_mfma_f32_32x32x16_bf16 v[80:95], v[220:223], v[244:247], v[80:95]
	ds_read_b128 v[220:223], v248 offset:18464
	v_mfma_f32_32x32x16_bf16 v[96:111], v[224:227], v[244:247], v[96:111]
	ds_read_b128 v[224:227], v248 offset:23072
	s_setprio 0
	s_waitcnt lgkmcnt(8)
	s_barrier
	v_max3_f32 v14, v80, v81, v82
	v_max3_f32 v15, v96, v97, v98
	v_max3_f32 v14, v14, v83, v84
	v_max3_f32 v15, v15, v99, v100
	v_max3_f32 v14, v14, v85, v86
	v_max3_f32 v15, v15, v101, v102
	v_max3_f32 v14, v14, v87, v88
	v_max3_f32 v15, v15, v103, v104
	v_max3_f32 v14, v14, v89, v90
	v_max3_f32 v15, v15, v105, v106
	v_max3_f32 v14, v14, v91, v92
	v_max3_f32 v15, v15, v107, v108
	v_max_f32_e32 v140, v111, v111
	v_max_f32_e32 v141, v95, v95
	v_max3_f32 v14, v14, v93, v94
	v_max3_f32 v15, v15, v109, v110
	v_max_f32_e32 v140, v141, v140
	v_max3_f32 v14, v14, v15, v140
	v_cmp_lt_f32_e32 vcc, s33, v14
	s_cbranch_vccnz .Lfd_b_resc
.Lfd_b_exp:
	v_exp_f32_e32 v80, v80
	v_exp_f32_e32 v96, v96
	v_exp_f32_e32 v81, v81
	v_exp_f32_e32 v97, v97
	v_exp_f32_e32 v88, v88
	v_exp_f32_e32 v104, v104
	v_exp_f32_e32 v89, v89
	v_exp_f32_e32 v105, v105
	v_exp_f32_e32 v82, v82
	v_exp_f32_e32 v98, v98
	v_exp_f32_e32 v83, v83
	v_exp_f32_e32 v99, v99
	v_exp_f32_e32 v90, v90
	v_exp_f32_e32 v106, v106
	v_exp_f32_e32 v91, v91
	v_exp_f32_e32 v107, v107
	v_exp_f32_e32 v84, v84
	v_exp_f32_e32 v100, v100
	v_exp_f32_e32 v85, v85
	v_exp_f32_e32 v101, v101
	v_exp_f32_e32 v92, v92
	v_exp_f32_e32 v108, v108
	v_exp_f32_e32 v93, v93
	v_exp_f32_e32 v109, v109
	v_exp_f32_e32 v86, v86
	v_exp_f32_e32 v102, v102
	v_exp_f32_e32 v87, v87
	v_exp_f32_e32 v103, v103
	v_exp_f32_e32 v94, v94
	v_exp_f32_e32 v110, v110
	v_exp_f32_e32 v95, v95
	v_exp_f32_e32 v111, v111
	v_pk_add_f32 v[140:141], v[80:81], v[96:97]
	v_pk_add_f32 v[142:143], v[82:83], v[98:99]
	v_pk_add_f32 v[144:145], v[84:85], v[100:101]
	v_pk_add_f32 v[146:147], v[86:87], v[102:103]
	v_pk_add_f32 v[148:149], v[88:89], v[104:105]
	v_pk_add_f32 v[150:151], v[90:91], v[106:107]
	v_pk_add_f32 v[152:153], v[92:93], v[108:109]
	v_pk_add_f32 v[154:155], v[94:95], v[110:111]
	v_pk_add_f32 v[140:141], v[140:141], v[142:143]
	v_pk_add_f32 v[144:145], v[144:145], v[146:147]
	v_pk_add_f32 v[148:149], v[148:149], v[150:151]
	v_pk_add_f32 v[152:153], v[152:153], v[154:155]
	v_pk_add_f32 v[140:141], v[140:141], v[144:145]
	v_pk_add_f32 v[148:149], v[148:149], v[152:153]
	v_pk_add_f32 v[140:141], v[140:141], v[148:149]
	v_add_f32_e32 v14, v140, v141
	v_cvt_pk_bf16_f32 v140, v80, v81
	v_cvt_pk_bf16_f32 v141, v82, v83
	v_cvt_pk_bf16_f32 v142, v84, v85
	v_cvt_pk_bf16_f32 v143, v86, v87
	v_cvt_pk_bf16_f32 v144, v88, v89
	v_cvt_pk_bf16_f32 v145, v90, v91
	v_cvt_pk_bf16_f32 v146, v92, v93
	v_cvt_pk_bf16_f32 v147, v94, v95
	v_cvt_pk_bf16_f32 v148, v96, v97
	v_cvt_pk_bf16_f32 v149, v98, v99
	v_cvt_pk_bf16_f32 v150, v100, v101
	v_cvt_pk_bf16_f32 v151, v102, v103
	v_cvt_pk_bf16_f32 v152, v104, v105
	v_cvt_pk_bf16_f32 v153, v106, v107
	v_cvt_pk_bf16_f32 v154, v108, v109
	v_cvt_pk_bf16_f32 v155, v110, v111
	v_add_f32_e32 v193, v193, v14
	s_waitcnt lgkmcnt(0)
	s_barrier
	v_mfma_f32_32x32x16_bf16 v[64:79], v[196:199], v[140:143], v[64:79]
	s_setprio 1
	v_add_u32_e32 v0, s51, v188
	s_waitcnt vmcnt(3)
	ds_write_b128 v0, v[10:13]
	v_mfma_f32_32x32x16_bf16 v[48:63], v[200:203], v[140:143], v[48:63]
	ds_read_b128 v[196:199], v248 offset:9280
	v_add_u32_e32 v0, s51, v186
	v_add_u32_e32 v10, v0, v175
	v_mfma_f32_32x32x16_bf16 v[32:47], v[204:207], v[140:143], v[32:47]
	ds_read_b128 v[200:203], v248 offset:13888
	v_add_u32_e32 v0, v0, v187
	ds_write_b128 v10, v[2:5] offset:9216
	v_mfma_f32_32x32x16_bf16 v[16:31], v[208:211], v[140:143], v[16:31]
	ds_read_b128 v[204:207], v248 offset:18496
	ds_write_b128 v0, v[6:9] offset:9216
	v_mfma_f32_32x32x16_bf16 v[64:79], v[212:215], v[144:147], v[64:79]
	ds_read_b128 v[208:211], v248 offset:23104
	v_add_u32_e32 v249, s50, v190
	v_mfma_f32_32x32x16_bf16 v[48:63], v[216:219], v[144:147], v[48:63]
	ds_read_b128 v[212:215], v248 offset:9312
	s_add_i32 s54, s54, 2
	s_mov_b32 s0, s51
	v_mfma_f32_32x32x16_bf16 v[32:47], v[220:223], v[144:147], v[32:47]
	ds_read_b128 v[216:219], v248 offset:13920
	s_mov_b32 s51, s50
	s_mov_b32 s50, s55
	v_mfma_f32_32x32x16_bf16 v[16:31], v[224:227], v[144:147], v[16:31]
	ds_read_b128 v[220:223], v248 offset:18528
	ds_read_b128 v[224:227], v248 offset:23136
	s_mov_b32 s55, s0
	s_addk_i32 s47, 0x80
	s_waitcnt lgkmcnt(4)
	v_mfma_f32_32x32x16_bf16 v[64:79], v[196:199], v[148:151], v[64:79]
	ds_read_b128 v[196:199], v249
	s_add_i32 s1, s54, 3
	s_lshl_b32 s8, s1, 6
	v_mfma_f32_32x32x16_bf16 v[48:63], v[200:203], v[148:151], v[48:63]
	ds_read_b128 v[200:203], v249 offset:4608
	v_add_u32_e32 v2, s8, v174
	v_ashrrev_i32_e32 v3, 31, v2
	v_mfma_f32_32x32x16_bf16 v[32:47], v[204:207], v[148:151], v[32:47]
	ds_read_b128 v[204:207], v249 offset:32
	v_lshlrev_b64 v[2:3], 10, v[2:3]
	v_lshl_add_u64 v[6:7], s[8:9], 1, v[176:177]
	v_mfma_f32_32x32x16_bf16 v[16:31], v[208:211], v[148:151], v[16:31]
	ds_read_b128 v[208:211], v249 offset:4640
	v_lshl_add_u64 v[2:3], v[182:183], 0, v[2:3]
	v_lshl_add_u64 v[4:5], v[6:7], 0, v[178:179]
	s_waitcnt lgkmcnt(4)
	v_mfma_f32_32x32x16_bf16 v[64:79], v[212:215], v[152:155], v[64:79]
	ds_read_b128 v[212:215], v249 offset:64
	v_lshl_add_u64 v[6:7], v[6:7], 0, v[180:181]
	global_load_dwordx4 v[10:13], v[2:3], off
	v_mfma_f32_32x32x16_bf16 v[48:63], v[216:219], v[152:155], v[48:63]
	ds_read_b128 v[216:219], v249 offset:4672
	s_nop 0
	global_load_dwordx4 v[2:5], v[4:5], off
	v_mfma_f32_32x32x16_bf16 v[32:47], v[220:223], v[152:155], v[32:47]
	ds_read_b128 v[220:223], v249 offset:96
	global_load_dwordx4 v[6:9], v[6:7], off
	v_mfma_f32_32x32x16_bf16 v[16:31], v[224:227], v[152:155], v[16:31]
	ds_read_b128 v[224:227], v249 offset:4704
	v_add_u32_e32 v248, s51, v190
	s_waitcnt lgkmcnt(4)
	v_mfma_f32_32x32x16_bf16 v[80:95], v[196:199], v[232:235], v[112:127]
	ds_read_b128 v[196:199], v248 offset:9216
	v_mfma_f32_32x32x16_bf16 v[96:111], v[200:203], v[232:235], v[112:127]
	ds_read_b128 v[200:203], v248 offset:13824
	v_mfma_f32_32x32x16_bf16 v[80:95], v[204:207], v[236:239], v[80:95]
	ds_read_b128 v[204:207], v248 offset:18432
	v_mfma_f32_32x32x16_bf16 v[96:111], v[208:211], v[236:239], v[96:111]
	ds_read_b128 v[208:211], v248 offset:23040
	s_waitcnt lgkmcnt(4)
	v_mfma_f32_32x32x16_bf16 v[80:95], v[212:215], v[240:243], v[80:95]
	ds_read_b128 v[212:215], v248 offset:9248
	v_mfma_f32_32x32x16_bf16 v[96:111], v[216:219], v[240:243], v[96:111]
	ds_read_b128 v[216:219], v248 offset:13856
	s_add_i32 s4, s48, s54
	v_mfma_f32_32x32x16_bf16 v[80:95], v[220:223], v[244:247], v[80:95]
	ds_read_b128 v[220:223], v248 offset:18464
	v_mfma_f32_32x32x16_bf16 v[96:111], v[224:227], v[244:247], v[96:111]
	ds_read_b128 v[224:227], v248 offset:23072
	s_cmp_lt_i32 s4, -2
	s_setprio 0
	s_waitcnt lgkmcnt(8)
	s_barrier
	s_cbranch_scc1 .Lfd_head
	s_mov_b32 s0, s51
	s_mov_b32 s51, s55
	s_branch .LBB0_1072
